# v8 + residual-GEMM epilogue: dependent parameter load round trips merged (head: 3 to 1, second column half: 3 to 1), counted waits
# speedup vs baseline: 1.0091x; 1.0034x over previous
; DI float hlo(unsigned u) { return (float)__builtin_bit_cast(f16x2_t, u).x; }
; DI float hhi(unsigned u) { return (float)__builtin_bit_cast(f16x2_t, u).y; }
;     DI void operator()(const pg8::f32x4 (&acc)[2][2][4][2], const pg8::Unit& u, int wr, int wc, int fr, int fq) const {
;         const int mi = (u.pm < 128) ? (u.pm >> 4) : 8;
;         const float* gp = modg + (size_t)mi * 9216;
;         const int row0 = u.pm * 256 + wr * 64 + fr, col0 = u.pn * 256 + wc * 32 + 8 * fq;
;         const float scale = *scale_p;
; #pragma unroll
;         for (int bj = 0; bj < 2; ++bj) {
;             f32x4 gs[2], gq[2], bq[2];
; #pragma unroll
;             for (int n = 0; n < 2; ++n) { const f32x4 g = *(const f32x4*)(gp + col0 + bj * 128 + 4 * n); gs[n] = (g + 1.0f) * scale;
;                 gq[n] = *(const f32x4*)(gprev + col0 + bj * 128 + 4 * n) * ALPHA; bq[n] = *(const f32x4*)(bprev + col0 + bj * 128 + 4 * n) * ALPHA; }
; #pragma unroll
;             for (int ai = 0; ai < 2; ++ai) {
;                 u32x4 xv[4]; f32x2 st[4];
; #pragma unroll
;                 for (int m = 0; m < 4; ++m) { const int row = row0 + ai * 128 + m * 16; xv[m] = *(const u32x4*)(X + (size_t)row * DM + col0 + bj * 128); st[m] = stat[row]; }
;                 __builtin_amdgcn_sched_barrier(0);
; #pragma unroll
;                 for (int m = 0; m < 4; ++m) {
;                     const f32x4 x0 = {hlo(xv[m].x), hhi(xv[m].x), hlo(xv[m].y), hhi(xv[m].y)}, x1 = {hlo(xv[m].z), hhi(xv[m].z), hlo(xv[m].w), hhi(xv[m].w)};
;                     const f32x4 y0 = (x0 - st[m].x) * st[m].y * gq[0] + bq[0] + gs[0] * acc[ai][bj][m][0];
.LBB0_886:
	s_lshl_b64 s[30:31], s[30:31], 2
	v_lshl_or_b32 v138, s56, 8, v225
	s_add_u32 s30, s46, s30
	v_ashrrev_i32_e32 v139, 31, v138
	s_addc_u32 s31, s47, s31
	v_lshlrev_b64 v[142:143], 2, v[138:139]
	v_lshl_add_u64 v[158:159], s[30:31], 0, v[142:143]
	global_load_dword v140, v147, s[6:7]
	global_load_dwordx4 v[160:163], v[158:159], off offset:16
	global_load_dwordx4 v[164:167], v[158:159], off
	v_lshl_add_u64 v[154:155], s[20:21], 0, v[142:143]
	v_lshl_add_u64 v[142:143], s[22:23], 0, v[142:143]
	global_load_dwordx4 v[204:207], v[154:155], off offset:16
	global_load_dwordx4 v[168:171], v[154:155], off
	global_load_dwordx4 v[228:231], v[142:143], off offset:16
	global_load_dwordx4 v[176:179], v[142:143], off
	s_mov_b32 s34, 0x3fd744fd
	v_lshl_add_u32 v202, s55, 8, v223
	v_lshlrev_b64 v[196:197], 1, v[138:139]
	v_ashrrev_i32_e32 v203, 31, v202
	v_lshl_add_u64 v[198:199], s[24:25], 0, v[196:197]
	v_lshlrev_b64 v[200:201], 11, v[202:203]
	v_lshl_add_u64 v[138:139], v[202:203], 3, s[26:27]
	s_waitcnt vmcnt(4)
	v_pk_add_f32 v[160:161], v[160:161], 1.0 op_sel_hi:[1,0]
	v_pk_add_f32 v[164:165], v[164:165], 1.0 op_sel_hi:[1,0]
	v_pk_add_f32 v[156:157], v[166:167], 1.0 op_sel_hi:[1,0]
	v_pk_mul_f32 v[174:175], v[140:141], v[164:165] op_sel_hi:[0,1]
	v_pk_mul_f32 v[172:173], v[140:141], v[156:157] op_sel_hi:[0,1]
	v_pk_add_f32 v[156:157], v[162:163], 1.0 op_sel_hi:[1,0]
	v_or_b32_e32 v162, 16, v202
	v_ashrrev_i32_e32 v163, 31, v162
	v_lshlrev_b64 v[246:247], 11, v[162:163]
	v_lshl_add_u64 v[162:163], v[162:163], 3, s[26:27]
	s_waitcnt vmcnt(3)
	v_pk_mul_f32 v[184:185], v[206:207], s[34:35] op_sel_hi:[1,0]
	s_waitcnt vmcnt(2)
	v_pk_mul_f32 v[180:181], v[170:171], s[34:35] op_sel_hi:[1,0]
	v_pk_mul_f32 v[182:183], v[168:169], s[34:35] op_sel_hi:[1,0]
	v_or_b32_e32 v206, 32, v202
	v_ashrrev_i32_e32 v207, 31, v206
	v_lshlrev_b64 v[150:151], 11, v[206:207]
	v_pk_mul_f32 v[186:187], v[204:205], s[34:35] op_sel_hi:[1,0]
	v_lshl_add_u64 v[204:205], v[198:199], 0, v[150:151]
	v_lshl_add_u64 v[206:207], v[206:207], 3, s[26:27]
	v_mov_b32_e32 v164, v204
	v_mov_b32_e32 v165, v205
	v_mov_b32_e32 v166, v206
	v_mov_b32_e32 v167, v207
	global_load_dwordx4 v[236:239], v[164:165], off
	global_load_dwordx2 v[206:207], v[166:167], off
	global_load_dwordx2 v[244:245], v[138:139], off
	global_load_dwordx2 v[248:249], v[162:163], off
	s_waitcnt vmcnt(5)
	v_pk_mul_f32 v[188:189], v[230:231], s[34:35] op_sel_hi:[1,0]
	v_or_b32_e32 v170, 48, v202
	v_ashrrev_i32_e32 v171, 31, v170
	v_lshlrev_b64 v[202:203], 11, v[170:171]
	s_waitcnt vmcnt(4)
	v_pk_mul_f32 v[192:193], v[178:179], s[34:35] op_sel_hi:[1,0]
	v_pk_mul_f32 v[194:195], v[176:177], s[34:35] op_sel_hi:[1,0]
	v_pk_mul_f32 v[176:177], v[140:141], v[156:157] op_sel_hi:[0,1]
	v_pk_mul_f32 v[178:179], v[140:141], v[160:161] op_sel_hi:[0,1]
	v_pk_mul_f32 v[190:191], v[228:229], s[34:35] op_sel_hi:[1,0]
	v_lshl_add_u64 v[156:157], v[198:199], 0, v[200:201]
	v_lshl_add_u64 v[160:161], v[198:199], 0, v[246:247]
	v_lshl_add_u64 v[168:169], v[198:199], 0, v[202:203]
	v_lshl_add_u64 v[170:171], v[170:171], 3, s[26:27]
	global_load_dwordx4 v[228:231], v[156:157], off
	global_load_dwordx4 v[232:235], v[160:161], off
	global_load_dwordx4 v[240:243], v[168:169], off
	global_load_dwordx2 v[204:205], v[170:171], off
	s_waitcnt vmcnt(3)
	v_cvt_f32_f16_sdwa v227, v228 dst_sel:DWORD dst_unused:UNUSED_PAD src0_sel:WORD_1
	v_cvt_f32_f16_e32 v228, v228
	v_cvt_f32_f16_sdwa v250, v229 dst_sel:DWORD dst_unused:UNUSED_PAD src0_sel:WORD_1
	v_cvt_f32_f16_e32 v145, v229
	v_cvt_f32_f16_sdwa v218, v230 dst_sel:DWORD dst_unused:UNUSED_PAD src0_sel:WORD_1
	v_cvt_f32_f16_e32 v209, v230
	v_cvt_f32_f16_sdwa v219, v231 dst_sel:DWORD dst_unused:UNUSED_PAD src0_sel:WORD_1
	v_cvt_f32_f16_e32 v220, v231
	v_sub_f32_e32 v228, v228, v244
	v_sub_f32_e32 v229, v227, v244
	v_sub_f32_e32 v230, v145, v244
	v_sub_f32_e32 v231, v250, v244
	v_pk_mul_f32 v[228:229], v[244:245], v[228:229] op_sel:[1,0]
	v_pk_mul_f32 v[230:231], v[244:245], v[230:231] op_sel:[1,0]
	v_pk_fma_f32 v[228:229], v[182:183], v[228:229], v[194:195]
	v_pk_fma_f32 v[230:231], v[180:181], v[230:231], v[192:193]
	v_pk_fma_f32 v[124:125], v[124:125], v[174:175], v[228:229]
	v_sub_f32_e32 v228, v209, v244
	v_sub_f32_e32 v229, v218, v244
	v_pk_fma_f32 v[126:127], v[126:127], v[172:173], v[230:231]
	v_sub_f32_e32 v230, v220, v244
	v_sub_f32_e32 v231, v219, v244
	v_pk_mul_f32 v[228:229], v[244:245], v[228:229] op_sel:[1,0]
	v_pk_mul_f32 v[230:231], v[244:245], v[230:231] op_sel:[1,0]
	v_pk_fma_f32 v[228:229], v[186:187], v[228:229], v[190:191]
	v_pk_fma_f32 v[230:231], v[184:185], v[230:231], v[188:189]
	v_pk_fma_f32 v[120:121], v[120:121], v[178:179], v[228:229]
	v_pk_fma_f32 v[230:231], v[122:123], v[176:177], v[230:231]
	v_cvt_pkrtz_f16_f32 v122, v124, v125
	v_cvt_pkrtz_f16_f32 v124, v120, v121
	v_lshl_add_u64 v[120:121], s[24:25], 0, v[200:201]
	v_cvt_pkrtz_f16_f32 v123, v126, v127
	v_cvt_pkrtz_f16_f32 v125, v230, v231
	v_lshl_add_u64 v[120:121], v[120:121], 0, v[196:197]
	global_store_dwordx4 v[120:121], v[122:125], off
	s_waitcnt vmcnt(3)
; DI unsigned pkh2(float lo, float hi) { return __builtin_bit_cast(unsigned, __builtin_amdgcn_cvt_pkrtz(lo, hi)); }
; DI float hlo(unsigned u) { return (float)__builtin_bit_cast(f16x2_t, u).x; }
; DI float hhi(unsigned u) { return (float)__builtin_bit_cast(f16x2_t, u).y; }
;     DI void operator()(const pg8::f32x4 (&acc)[2][2][4][2], const pg8::Unit& u, int wr, int wc, int fr, int fq) const {
;     ...
;                 for (int m = 0; m < 4; ++m) { const int row = row0 + ai * 128 + m * 16; xv[m] = *(const u32x4*)(X + (size_t)row * DM + col0 + bj * 128); st[m] = stat[row]; }
;                 __builtin_amdgcn_sched_barrier(0);
; #pragma unroll
;                 for (int m = 0; m < 4; ++m) {
;                     const f32x4 x0 = {hlo(xv[m].x), hhi(xv[m].x), hlo(xv[m].y), hhi(xv[m].y)}, x1 = {hlo(xv[m].z), hhi(xv[m].z), hlo(xv[m].w), hhi(xv[m].w)};
;                     const f32x4 y0 = (x0 - st[m].x) * st[m].y * gq[0] + bq[0] + gs[0] * acc[ai][bj][m][0];
;                     const f32x4 y1 = (x1 - st[m].x) * st[m].y * gq[1] + bq[1] + gs[1] * acc[ai][bj][m][1];
;                     u32x4 w; w.x = pkh2(y0.x, y0.y); w.y = pkh2(y0.z, y0.w); w.z = pkh2(y1.x, y1.y); w.w = pkh2(y1.z, y1.w);
;                     *(u32x4*)(X + (size_t)(row0 + ai * 128 + m * 16) * DM + col0 + bj * 128) = w;
;                 }
	v_cvt_f32_f16_sdwa v126, v234 dst_sel:DWORD dst_unused:UNUSED_PAD src0_sel:WORD_1
	v_cvt_f32_f16_e32 v127, v234
	v_cvt_f32_f16_sdwa v123, v232 dst_sel:DWORD dst_unused:UNUSED_PAD src0_sel:WORD_1
	v_cvt_f32_f16_e32 v122, v232
	v_cvt_f32_f16_sdwa v125, v233 dst_sel:DWORD dst_unused:UNUSED_PAD src0_sel:WORD_1
	v_cvt_f32_f16_e32 v124, v233
	v_cvt_f32_f16_sdwa v145, v235 dst_sel:DWORD dst_unused:UNUSED_PAD src0_sel:WORD_1
	v_cvt_f32_f16_e32 v209, v235
	v_sub_f32_e32 v122, v122, v248
	v_sub_f32_e32 v123, v123, v248
	v_sub_f32_e32 v124, v124, v248
	v_sub_f32_e32 v125, v125, v248
	v_pk_mul_f32 v[122:123], v[248:249], v[122:123] op_sel:[1,0]
	v_pk_mul_f32 v[124:125], v[248:249], v[124:125] op_sel:[1,0]
	v_pk_fma_f32 v[122:123], v[182:183], v[122:123], v[194:195]
	v_pk_fma_f32 v[124:125], v[180:181], v[124:125], v[192:193]
	v_pk_fma_f32 v[116:117], v[116:117], v[174:175], v[122:123]
	v_sub_f32_e32 v122, v127, v248
	v_sub_f32_e32 v123, v126, v248
	v_pk_fma_f32 v[118:119], v[118:119], v[172:173], v[124:125]
	v_sub_f32_e32 v124, v209, v248
	v_sub_f32_e32 v125, v145, v248
	v_pk_mul_f32 v[122:123], v[248:249], v[122:123] op_sel:[1,0]
	v_pk_mul_f32 v[124:125], v[248:249], v[124:125] op_sel:[1,0]
	v_pk_fma_f32 v[122:123], v[186:187], v[122:123], v[190:191]
	v_pk_fma_f32 v[124:125], v[184:185], v[124:125], v[188:189]
	v_pk_fma_f32 v[112:113], v[112:113], v[178:179], v[122:123]
	v_pk_fma_f32 v[124:125], v[114:115], v[176:177], v[124:125]
	v_cvt_pkrtz_f16_f32 v114, v116, v117
	v_cvt_pkrtz_f16_f32 v116, v112, v113
	v_lshl_add_u64 v[112:113], s[24:25], 0, v[246:247]
	v_cvt_pkrtz_f16_f32 v115, v118, v119
	v_cvt_pkrtz_f16_f32 v117, v124, v125
	v_lshl_add_u64 v[112:113], v[112:113], 0, v[196:197]
	global_store_dwordx4 v[112:113], v[114:117], off
	v_cvt_f32_f16_sdwa v118, v238 dst_sel:DWORD dst_unused:UNUSED_PAD src0_sel:WORD_1
	v_cvt_f32_f16_e32 v119, v238
	v_cvt_f32_f16_sdwa v115, v236 dst_sel:DWORD dst_unused:UNUSED_PAD src0_sel:WORD_1
	v_cvt_f32_f16_e32 v114, v236
	v_cvt_f32_f16_sdwa v117, v237 dst_sel:DWORD dst_unused:UNUSED_PAD src0_sel:WORD_1
	v_cvt_f32_f16_e32 v116, v237
	v_cvt_f32_f16_sdwa v122, v239 dst_sel:DWORD dst_unused:UNUSED_PAD src0_sel:WORD_1
	v_cvt_f32_f16_e32 v123, v239
	v_sub_f32_e32 v114, v114, v206
	v_sub_f32_e32 v115, v115, v206
	v_sub_f32_e32 v116, v116, v206
	v_sub_f32_e32 v117, v117, v206
	v_pk_mul_f32 v[114:115], v[206:207], v[114:115] op_sel:[1,0]
	v_pk_mul_f32 v[116:117], v[206:207], v[116:117] op_sel:[1,0]
	v_pk_fma_f32 v[114:115], v[182:183], v[114:115], v[194:195]
	v_pk_fma_f32 v[116:117], v[180:181], v[116:117], v[192:193]
	v_pk_fma_f32 v[108:109], v[108:109], v[174:175], v[114:115]
	v_sub_f32_e32 v114, v119, v206
	v_sub_f32_e32 v115, v118, v206
	v_pk_fma_f32 v[110:111], v[110:111], v[172:173], v[116:117]
	v_sub_f32_e32 v116, v123, v206
	v_sub_f32_e32 v117, v122, v206
	v_pk_mul_f32 v[114:115], v[206:207], v[114:115] op_sel:[1,0]
	v_pk_mul_f32 v[116:117], v[206:207], v[116:117] op_sel:[1,0]
	v_pk_fma_f32 v[114:115], v[186:187], v[114:115], v[190:191]
	v_pk_fma_f32 v[116:117], v[184:185], v[116:117], v[188:189]
	v_pk_fma_f32 v[104:105], v[104:105], v[178:179], v[114:115]
	v_pk_fma_f32 v[116:117], v[106:107], v[176:177], v[116:117]
	v_cvt_pkrtz_f16_f32 v106, v108, v109
	v_cvt_pkrtz_f16_f32 v108, v104, v105
	v_lshl_add_u64 v[104:105], s[24:25], 0, v[150:151]
	v_cvt_pkrtz_f16_f32 v107, v110, v111
	v_cvt_pkrtz_f16_f32 v109, v116, v117
	v_lshl_add_u64 v[104:105], v[104:105], 0, v[196:197]
	global_store_dwordx4 v[104:105], v[106:109], off
	s_waitcnt vmcnt(4)
	v_cvt_f32_f16_sdwa v110, v242 dst_sel:DWORD dst_unused:UNUSED_PAD src0_sel:WORD_1
	v_cvt_f32_f16_e32 v111, v242
	v_cvt_f32_f16_sdwa v107, v240 dst_sel:DWORD dst_unused:UNUSED_PAD src0_sel:WORD_1
	v_cvt_f32_f16_e32 v106, v240
	v_cvt_f32_f16_sdwa v109, v241 dst_sel:DWORD dst_unused:UNUSED_PAD src0_sel:WORD_1
	v_cvt_f32_f16_e32 v108, v241
	v_cvt_f32_f16_sdwa v114, v243 dst_sel:DWORD dst_unused:UNUSED_PAD src0_sel:WORD_1
	v_cvt_f32_f16_e32 v115, v243
	s_waitcnt vmcnt(3)
	v_sub_f32_e32 v106, v106, v204
	v_sub_f32_e32 v107, v107, v204
	v_sub_f32_e32 v108, v108, v204
	v_sub_f32_e32 v109, v109, v204
	v_pk_mul_f32 v[106:107], v[204:205], v[106:107] op_sel:[1,0]
	v_pk_mul_f32 v[108:109], v[204:205], v[108:109] op_sel:[1,0]
	v_pk_fma_f32 v[106:107], v[182:183], v[106:107], v[194:195]
	v_pk_fma_f32 v[108:109], v[180:181], v[108:109], v[192:193]
	v_pk_fma_f32 v[100:101], v[100:101], v[174:175], v[106:107]
	v_sub_f32_e32 v106, v111, v204
	v_sub_f32_e32 v107, v110, v204
	v_pk_fma_f32 v[102:103], v[102:103], v[172:173], v[108:109]
	v_sub_f32_e32 v108, v115, v204
	v_sub_f32_e32 v109, v114, v204
	v_pk_mul_f32 v[106:107], v[204:205], v[106:107] op_sel:[1,0]
	v_pk_mul_f32 v[108:109], v[204:205], v[108:109] op_sel:[1,0]
	v_pk_fma_f32 v[106:107], v[186:187], v[106:107], v[190:191]
	v_pk_fma_f32 v[108:109], v[184:185], v[108:109], v[188:189]
	v_pk_fma_f32 v[96:97], v[96:97], v[178:179], v[106:107]
	v_pk_fma_f32 v[108:109], v[98:99], v[176:177], v[108:109]
	v_cvt_pkrtz_f16_f32 v98, v100, v101
	v_cvt_pkrtz_f16_f32 v100, v96, v97
	v_lshl_add_u64 v[96:97], s[24:25], 0, v[202:203]
	v_cvt_pkrtz_f16_f32 v99, v102, v103
	v_cvt_pkrtz_f16_f32 v101, v108, v109
	v_lshl_add_u64 v[96:97], v[96:97], 0, v[196:197]
	global_store_dwordx4 v[96:97], v[98:101], off
	s_mov_b64 s[30:31], 0x40000
	v_lshl_add_u64 v[118:119], v[200:201], 0, s[30:31]
	s_mov_b64 s[30:31], 0x48000
	v_lshl_add_u64 v[126:127], v[200:201], 0, s[30:31]
	s_mov_b64 s[30:31], 0x50000
	v_lshl_add_u64 v[150:151], v[200:201], 0, s[30:31]
	s_mov_b64 s[30:31], 0x58000
	v_lshl_add_u64 v[98:99], v[198:199], 0, v[118:119]
	v_lshl_add_u64 v[102:103], v[198:199], 0, v[150:151]
	v_lshl_add_u64 v[202:203], v[200:201], 0, s[30:31]
	v_lshl_add_u64 v[100:101], v[198:199], 0, v[126:127]
	global_load_dwordx4 v[108:111], v[98:99], off
	global_load_dwordx4 v[114:117], v[100:101], off
	v_lshl_add_u64 v[106:107], v[198:199], 0, v[202:203]
	global_load_dwordx4 v[122:125], v[102:103], off
	global_load_dwordx4 v[198:201], v[106:107], off
	global_load_dwordx2 v[204:205], v[138:139], off offset:1024
	global_load_dwordx2 v[206:207], v[138:139], off offset:1152
	global_load_dwordx2 v[228:229], v[138:139], off offset:1280
	global_load_dwordx2 v[230:231], v[138:139], off offset:1408
	s_waitcnt vmcnt(7)
; DI unsigned pkh2(float lo, float hi) { return __builtin_bit_cast(unsigned, __builtin_amdgcn_cvt_pkrtz(lo, hi)); }
; DI float hlo(unsigned u) { return (float)__builtin_bit_cast(f16x2_t, u).x; }
; DI float hhi(unsigned u) { return (float)__builtin_bit_cast(f16x2_t, u).y; }
;     DI void operator()(const pg8::f32x4 (&acc)[2][2][4][2], const pg8::Unit& u, int wr, int wc, int fr, int fq) const {
;     ...
;                 for (int m = 0; m < 4; ++m) { const int row = row0 + ai * 128 + m * 16; xv[m] = *(const u32x4*)(X + (size_t)row * DM + col0 + bj * 128); st[m] = stat[row]; }
;                 __builtin_amdgcn_sched_barrier(0);
; #pragma unroll
;                 for (int m = 0; m < 4; ++m) {
;                     const f32x4 x0 = {hlo(xv[m].x), hhi(xv[m].x), hlo(xv[m].y), hhi(xv[m].y)}, x1 = {hlo(xv[m].z), hhi(xv[m].z), hlo(xv[m].w), hhi(xv[m].w)};
;                     const f32x4 y0 = (x0 - st[m].x) * st[m].y * gq[0] + bq[0] + gs[0] * acc[ai][bj][m][0];
;                     const f32x4 y1 = (x1 - st[m].x) * st[m].y * gq[1] + bq[1] + gs[1] * acc[ai][bj][m][1];
;                     u32x4 w; w.x = pkh2(y0.x, y0.y); w.y = pkh2(y0.z, y0.w); w.z = pkh2(y1.x, y1.y); w.w = pkh2(y1.z, y1.w);
;                     *(u32x4*)(X + (size_t)(row0 + ai * 128 + m * 16) * DM + col0 + bj * 128) = w;
;                 }
	v_cvt_f32_f16_sdwa v145, v108 dst_sel:DWORD dst_unused:UNUSED_PAD src0_sel:WORD_1
	v_cvt_f32_f16_e32 v108, v108
	v_cvt_f32_f16_sdwa v209, v109 dst_sel:DWORD dst_unused:UNUSED_PAD src0_sel:WORD_1
	v_cvt_f32_f16_e32 v218, v109
	v_cvt_f32_f16_sdwa v219, v110 dst_sel:DWORD dst_unused:UNUSED_PAD src0_sel:WORD_1
	v_cvt_f32_f16_e32 v220, v110
	v_cvt_f32_f16_sdwa v227, v111 dst_sel:DWORD dst_unused:UNUSED_PAD src0_sel:WORD_1
	v_cvt_f32_f16_e32 v232, v111
	s_waitcnt vmcnt(3)
	v_sub_f32_e32 v108, v108, v204
	v_sub_f32_e32 v109, v145, v204
	v_sub_f32_e32 v110, v218, v204
	v_sub_f32_e32 v111, v209, v204
	v_pk_mul_f32 v[108:109], v[204:205], v[108:109] op_sel:[1,0]
	v_pk_mul_f32 v[110:111], v[204:205], v[110:111] op_sel:[1,0]
	v_pk_fma_f32 v[108:109], v[182:183], v[108:109], v[194:195]
	v_pk_fma_f32 v[110:111], v[180:181], v[110:111], v[192:193]
	v_pk_fma_f32 v[92:93], v[92:93], v[174:175], v[108:109]
	v_sub_f32_e32 v108, v220, v204
	v_sub_f32_e32 v109, v219, v204
	v_pk_fma_f32 v[94:95], v[94:95], v[172:173], v[110:111]
	v_sub_f32_e32 v110, v232, v204
	v_sub_f32_e32 v111, v227, v204
	v_pk_mul_f32 v[108:109], v[204:205], v[108:109] op_sel:[1,0]
	v_pk_mul_f32 v[110:111], v[204:205], v[110:111] op_sel:[1,0]
	v_pk_fma_f32 v[108:109], v[186:187], v[108:109], v[190:191]
	v_pk_fma_f32 v[110:111], v[184:185], v[110:111], v[188:189]
	v_pk_fma_f32 v[88:89], v[88:89], v[178:179], v[108:109]
	v_pk_fma_f32 v[110:111], v[90:91], v[176:177], v[110:111]
	v_cvt_pkrtz_f16_f32 v90, v92, v93
	v_cvt_pkrtz_f16_f32 v92, v88, v89
	v_lshl_add_u64 v[88:89], s[24:25], 0, v[118:119]
	v_cvt_pkrtz_f16_f32 v91, v94, v95
	v_cvt_pkrtz_f16_f32 v93, v110, v111
	v_lshl_add_u64 v[88:89], v[88:89], 0, v[196:197]
	global_store_dwordx4 v[88:89], v[90:93], off
	v_cvt_f32_f16_sdwa v94, v116 dst_sel:DWORD dst_unused:UNUSED_PAD src0_sel:WORD_1
	v_cvt_f32_f16_e32 v95, v116
	v_cvt_f32_f16_sdwa v91, v114 dst_sel:DWORD dst_unused:UNUSED_PAD src0_sel:WORD_1
	v_cvt_f32_f16_e32 v90, v114
	v_cvt_f32_f16_sdwa v93, v115 dst_sel:DWORD dst_unused:UNUSED_PAD src0_sel:WORD_1
	v_cvt_f32_f16_e32 v92, v115
	v_cvt_f32_f16_sdwa v108, v117 dst_sel:DWORD dst_unused:UNUSED_PAD src0_sel:WORD_1
	v_cvt_f32_f16_e32 v109, v117
	s_waitcnt vmcnt(3)
	v_sub_f32_e32 v90, v90, v206
	v_sub_f32_e32 v91, v91, v206
	v_sub_f32_e32 v92, v92, v206
	v_sub_f32_e32 v93, v93, v206
	v_pk_mul_f32 v[90:91], v[206:207], v[90:91] op_sel:[1,0]
	v_pk_mul_f32 v[92:93], v[206:207], v[92:93] op_sel:[1,0]
	v_pk_fma_f32 v[90:91], v[182:183], v[90:91], v[194:195]
	v_pk_fma_f32 v[92:93], v[180:181], v[92:93], v[192:193]
	v_pk_fma_f32 v[84:85], v[84:85], v[174:175], v[90:91]
	v_sub_f32_e32 v90, v95, v206
	v_sub_f32_e32 v91, v94, v206
	v_pk_fma_f32 v[86:87], v[86:87], v[172:173], v[92:93]
	v_sub_f32_e32 v92, v109, v206
	v_sub_f32_e32 v93, v108, v206
	v_pk_mul_f32 v[90:91], v[206:207], v[90:91] op_sel:[1,0]
	v_pk_mul_f32 v[92:93], v[206:207], v[92:93] op_sel:[1,0]
	v_pk_fma_f32 v[90:91], v[186:187], v[90:91], v[190:191]
	v_pk_fma_f32 v[92:93], v[184:185], v[92:93], v[188:189]
	v_pk_fma_f32 v[80:81], v[80:81], v[178:179], v[90:91]
	v_pk_fma_f32 v[92:93], v[82:83], v[176:177], v[92:93]
	v_cvt_pkrtz_f16_f32 v82, v84, v85
	v_cvt_pkrtz_f16_f32 v84, v80, v81
	v_lshl_add_u64 v[80:81], s[24:25], 0, v[126:127]
	v_cvt_pkrtz_f16_f32 v83, v86, v87
	v_cvt_pkrtz_f16_f32 v85, v92, v93
	v_lshl_add_u64 v[80:81], v[80:81], 0, v[196:197]
	global_store_dwordx4 v[80:81], v[82:85], off
	v_cvt_f32_f16_sdwa v86, v124 dst_sel:DWORD dst_unused:UNUSED_PAD src0_sel:WORD_1
	v_cvt_f32_f16_e32 v87, v124
	v_cvt_f32_f16_sdwa v83, v122 dst_sel:DWORD dst_unused:UNUSED_PAD src0_sel:WORD_1
	v_cvt_f32_f16_e32 v82, v122
	v_cvt_f32_f16_sdwa v85, v123 dst_sel:DWORD dst_unused:UNUSED_PAD src0_sel:WORD_1
	v_cvt_f32_f16_e32 v84, v123
	v_cvt_f32_f16_sdwa v90, v125 dst_sel:DWORD dst_unused:UNUSED_PAD src0_sel:WORD_1
	v_cvt_f32_f16_e32 v91, v125
	s_waitcnt vmcnt(3)
	v_sub_f32_e32 v82, v82, v228
	v_sub_f32_e32 v83, v83, v228
	v_sub_f32_e32 v84, v84, v228
	v_sub_f32_e32 v85, v85, v228
	v_pk_mul_f32 v[82:83], v[228:229], v[82:83] op_sel:[1,0]
	v_pk_mul_f32 v[84:85], v[228:229], v[84:85] op_sel:[1,0]
	v_pk_fma_f32 v[82:83], v[182:183], v[82:83], v[194:195]
	v_pk_fma_f32 v[84:85], v[180:181], v[84:85], v[192:193]
	v_pk_fma_f32 v[76:77], v[76:77], v[174:175], v[82:83]
	v_sub_f32_e32 v82, v87, v228
	v_sub_f32_e32 v83, v86, v228
	v_pk_fma_f32 v[78:79], v[78:79], v[172:173], v[84:85]
	v_sub_f32_e32 v84, v91, v228
	v_sub_f32_e32 v85, v90, v228
	v_pk_mul_f32 v[82:83], v[228:229], v[82:83] op_sel:[1,0]
	v_pk_mul_f32 v[84:85], v[228:229], v[84:85] op_sel:[1,0]
	v_pk_fma_f32 v[82:83], v[186:187], v[82:83], v[190:191]
	v_pk_fma_f32 v[84:85], v[184:185], v[84:85], v[188:189]
	v_pk_fma_f32 v[72:73], v[72:73], v[178:179], v[82:83]
	v_pk_fma_f32 v[84:85], v[74:75], v[176:177], v[84:85]
	v_cvt_pkrtz_f16_f32 v74, v76, v77
	v_cvt_pkrtz_f16_f32 v76, v72, v73
	v_lshl_add_u64 v[72:73], s[24:25], 0, v[150:151]
	v_cvt_pkrtz_f16_f32 v75, v78, v79
	v_cvt_pkrtz_f16_f32 v77, v84, v85
	v_lshl_add_u64 v[72:73], v[72:73], 0, v[196:197]
	global_store_dwordx4 v[72:73], v[74:77], off
	v_cvt_f32_f16_sdwa v78, v200 dst_sel:DWORD dst_unused:UNUSED_PAD src0_sel:WORD_1
	v_cvt_f32_f16_e32 v79, v200
	v_cvt_f32_f16_sdwa v75, v198 dst_sel:DWORD dst_unused:UNUSED_PAD src0_sel:WORD_1
	v_cvt_f32_f16_e32 v74, v198
	v_cvt_f32_f16_sdwa v77, v199 dst_sel:DWORD dst_unused:UNUSED_PAD src0_sel:WORD_1
	v_cvt_f32_f16_e32 v76, v199
	v_cvt_f32_f16_sdwa v82, v201 dst_sel:DWORD dst_unused:UNUSED_PAD src0_sel:WORD_1
	v_cvt_f32_f16_e32 v83, v201
	s_waitcnt vmcnt(3)
; DI unsigned pkh2(float lo, float hi) { return __builtin_bit_cast(unsigned, __builtin_amdgcn_cvt_pkrtz(lo, hi)); }
; DI float hlo(unsigned u) { return (float)__builtin_bit_cast(f16x2_t, u).x; }
; DI float hhi(unsigned u) { return (float)__builtin_bit_cast(f16x2_t, u).y; }
;     DI void operator()(const pg8::f32x4 (&acc)[2][2][4][2], const pg8::Unit& u, int wr, int wc, int fr, int fq) const {
;     ...
;             for (int n = 0; n < 2; ++n) { const f32x4 g = *(const f32x4*)(gp + col0 + bj * 128 + 4 * n); gs[n] = (g + 1.0f) * scale;
;                 gq[n] = *(const f32x4*)(gprev + col0 + bj * 128 + 4 * n) * ALPHA; bq[n] = *(const f32x4*)(bprev + col0 + bj * 128 + 4 * n) * ALPHA; }
; #pragma unroll
;             for (int ai = 0; ai < 2; ++ai) {
;                 u32x4 xv[4]; f32x2 st[4];
; #pragma unroll
;                 for (int m = 0; m < 4; ++m) { const int row = row0 + ai * 128 + m * 16; xv[m] = *(const u32x4*)(X + (size_t)row * DM + col0 + bj * 128); st[m] = stat[row]; }
;                 __builtin_amdgcn_sched_barrier(0);
; #pragma unroll
;                 for (int m = 0; m < 4; ++m) {
;                     const f32x4 x0 = {hlo(xv[m].x), hhi(xv[m].x), hlo(xv[m].y), hhi(xv[m].y)}, x1 = {hlo(xv[m].z), hhi(xv[m].z), hlo(xv[m].w), hhi(xv[m].w)};
;                     const f32x4 y0 = (x0 - st[m].x) * st[m].y * gq[0] + bq[0] + gs[0] * acc[ai][bj][m][0];
;                     const f32x4 y1 = (x1 - st[m].x) * st[m].y * gq[1] + bq[1] + gs[1] * acc[ai][bj][m][1];
;                     u32x4 w; w.x = pkh2(y0.x, y0.y); w.y = pkh2(y0.z, y0.w); w.z = pkh2(y1.x, y1.y); w.w = pkh2(y1.z, y1.w);
;                     *(u32x4*)(X + (size_t)(row0 + ai * 128 + m * 16) * DM + col0 + bj * 128) = w;
;                 }
	v_sub_f32_e32 v74, v74, v230
	v_sub_f32_e32 v75, v75, v230
	v_sub_f32_e32 v76, v76, v230
	v_sub_f32_e32 v77, v77, v230
	v_pk_mul_f32 v[74:75], v[230:231], v[74:75] op_sel:[1,0]
	v_pk_mul_f32 v[76:77], v[230:231], v[76:77] op_sel:[1,0]
	v_pk_fma_f32 v[74:75], v[182:183], v[74:75], v[194:195]
	v_pk_fma_f32 v[76:77], v[180:181], v[76:77], v[192:193]
	v_pk_fma_f32 v[68:69], v[68:69], v[174:175], v[74:75]
	v_sub_f32_e32 v74, v79, v230
	v_sub_f32_e32 v75, v78, v230
	v_pk_fma_f32 v[70:71], v[70:71], v[172:173], v[76:77]
	v_sub_f32_e32 v76, v83, v230
	v_sub_f32_e32 v77, v82, v230
	v_pk_mul_f32 v[74:75], v[230:231], v[74:75] op_sel:[1,0]
	v_pk_mul_f32 v[76:77], v[230:231], v[76:77] op_sel:[1,0]
	v_pk_fma_f32 v[74:75], v[186:187], v[74:75], v[190:191]
	v_pk_fma_f32 v[76:77], v[184:185], v[76:77], v[188:189]
	v_pk_fma_f32 v[64:65], v[64:65], v[178:179], v[74:75]
	v_pk_fma_f32 v[76:77], v[66:67], v[176:177], v[76:77]
	v_cvt_pkrtz_f16_f32 v66, v68, v69
	v_cvt_pkrtz_f16_f32 v68, v64, v65
	v_lshl_add_u64 v[64:65], s[24:25], 0, v[202:203]
	v_cvt_pkrtz_f16_f32 v67, v70, v71
	v_cvt_pkrtz_f16_f32 v69, v76, v77
	v_lshl_add_u64 v[64:65], v[64:65], 0, v[196:197]
	global_store_dwordx4 v[64:65], v[66:69], off
	global_load_dwordx4 v[76:79], v[158:159], off offset:528
	global_load_dwordx4 v[66:69], v[158:159], off offset:512
	global_load_dwordx4 v[84:87], v[154:155], off offset:528
	global_load_dwordx4 v[90:93], v[154:155], off offset:512
	global_load_dwordx4 v[108:111], v[142:143], off offset:528
	global_load_dwordx4 v[172:175], v[142:143], off offset:512
	global_load_dwordx4 v[176:179], v[156:157], off offset:256
	global_load_dwordx2 v[118:119], v[138:139], off
	global_load_dwordx4 v[114:117], v[160:161], off offset:256
	global_load_dwordx2 v[126:127], v[162:163], off
	global_load_dwordx4 v[122:125], v[164:165], off offset:256
	global_load_dwordx2 v[142:143], v[166:167], off
	global_load_dwordx4 v[154:157], v[168:169], off offset:256
	global_load_dwordx2 v[150:151], v[170:171], off
	s_nop 0
	s_waitcnt vmcnt(13)
	v_pk_add_f32 v[78:79], v[78:79], 1.0 op_sel_hi:[1,0]
	s_waitcnt vmcnt(12)
	v_pk_add_f32 v[68:69], v[68:69], 1.0 op_sel_hi:[1,0]
	v_pk_add_f32 v[70:71], v[66:67], 1.0 op_sel_hi:[1,0]
	v_pk_mul_f32 v[66:67], v[140:141], v[68:69] op_sel_hi:[0,1]
	v_pk_mul_f32 v[68:69], v[140:141], v[70:71] op_sel_hi:[0,1]
	s_waitcnt vmcnt(10)
	v_pk_mul_f32 v[70:71], v[92:93], s[34:35] op_sel_hi:[1,0]
	v_pk_mul_f32 v[74:75], v[90:91], s[34:35] op_sel_hi:[1,0]
	v_pk_add_f32 v[82:83], v[76:77], 1.0 op_sel_hi:[1,0]
	v_pk_mul_f32 v[76:77], v[140:141], v[78:79] op_sel_hi:[0,1]
	v_pk_mul_f32 v[78:79], v[140:141], v[82:83] op_sel_hi:[0,1]
	v_pk_mul_f32 v[82:83], v[86:87], s[34:35] op_sel_hi:[1,0]
	v_pk_mul_f32 v[84:85], v[84:85], s[34:35] op_sel_hi:[1,0]
	s_waitcnt vmcnt(9)
	v_pk_mul_f32 v[86:87], v[110:111], s[34:35] op_sel_hi:[1,0]
	s_waitcnt vmcnt(8)
	v_pk_mul_f32 v[94:95], v[172:173], s[34:35] op_sel_hi:[1,0]
	v_pk_mul_f32 v[172:173], v[108:109], s[34:35] op_sel_hi:[1,0]
	v_pk_mul_f32 v[174:175], v[174:175], s[34:35] op_sel_hi:[1,0]
	v_mov_b32_e32 v90, v172
	v_mov_b32_e32 v91, v173
	v_mov_b32_e32 v92, v174
	v_mov_b32_e32 v93, v175
	s_waitcnt vmcnt(7)
	v_cvt_f32_f16_sdwa v140, v176 dst_sel:DWORD dst_unused:UNUSED_PAD src0_sel:WORD_1
	v_cvt_f32_f16_e32 v108, v176
	v_cvt_f32_f16_sdwa v145, v177 dst_sel:DWORD dst_unused:UNUSED_PAD src0_sel:WORD_1
	v_cvt_f32_f16_e32 v158, v177
	v_cvt_f32_f16_sdwa v159, v178 dst_sel:DWORD dst_unused:UNUSED_PAD src0_sel:WORD_1
	v_cvt_f32_f16_e32 v160, v178
	v_cvt_f32_f16_sdwa v161, v179 dst_sel:DWORD dst_unused:UNUSED_PAD src0_sel:WORD_1
	v_cvt_f32_f16_e32 v162, v179
	s_waitcnt vmcnt(6)
	v_sub_f32_e32 v108, v108, v118
	v_sub_f32_e32 v109, v140, v118
	v_sub_f32_e32 v110, v158, v118
	v_sub_f32_e32 v111, v145, v118
	v_pk_mul_f32 v[110:111], v[118:119], v[110:111] op_sel:[1,0]
	v_pk_mul_f32 v[108:109], v[118:119], v[108:109] op_sel:[1,0]
	v_pk_fma_f32 v[110:111], v[70:71], v[110:111], v[92:93]
	v_pk_fma_f32 v[108:109], v[74:75], v[108:109], v[94:95]
	v_pk_fma_f32 v[62:63], v[62:63], v[66:67], v[110:111]
	v_pk_fma_f32 v[60:61], v[60:61], v[68:69], v[108:109]
	v_sub_f32_e32 v108, v160, v118
	v_sub_f32_e32 v109, v159, v118
	v_sub_f32_e32 v110, v162, v118
	v_sub_f32_e32 v111, v161, v118
	v_pk_mul_f32 v[110:111], v[118:119], v[110:111] op_sel:[1,0]
	v_pk_mul_f32 v[108:109], v[118:119], v[108:109] op_sel:[1,0]
	v_pk_fma_f32 v[110:111], v[82:83], v[110:111], v[86:87]
	v_pk_fma_f32 v[108:109], v[84:85], v[108:109], v[90:91]
	v_pk_fma_f32 v[110:111], v[58:59], v[76:77], v[110:111]
	v_pk_fma_f32 v[58:59], v[56:57], v[78:79], v[108:109]
	v_cvt_pkrtz_f16_f32 v56, v60, v61
	v_cvt_pkrtz_f16_f32 v57, v62, v63
	v_cvt_pkrtz_f16_f32 v58, v58, v59
	v_cvt_pkrtz_f16_f32 v59, v110, v111
	global_store_dwordx4 v[120:121], v[56:59], off offset:256
	s_waitcnt vmcnt(6)
	v_cvt_f32_f16_sdwa v60, v116 dst_sel:DWORD dst_unused:UNUSED_PAD src0_sel:WORD_1
	v_cvt_f32_f16_e32 v61, v116
	v_cvt_f32_f16_sdwa v57, v114 dst_sel:DWORD dst_unused:UNUSED_PAD src0_sel:WORD_1
	v_cvt_f32_f16_e32 v56, v114
	v_cvt_f32_f16_sdwa v59, v115 dst_sel:DWORD dst_unused:UNUSED_PAD src0_sel:WORD_1
	v_cvt_f32_f16_e32 v58, v115
	v_cvt_f32_f16_sdwa v62, v117 dst_sel:DWORD dst_unused:UNUSED_PAD src0_sel:WORD_1
	v_cvt_f32_f16_e32 v63, v117
	s_waitcnt vmcnt(5)
; DI unsigned pkh2(float lo, float hi) { return __builtin_bit_cast(unsigned, __builtin_amdgcn_cvt_pkrtz(lo, hi)); }
; DI float hlo(unsigned u) { return (float)__builtin_bit_cast(f16x2_t, u).x; }
; DI float hhi(unsigned u) { return (float)__builtin_bit_cast(f16x2_t, u).y; }
;     DI void operator()(const pg8::f32x4 (&acc)[2][2][4][2], const pg8::Unit& u, int wr, int wc, int fr, int fq) const {
;     ...
;                 for (int m = 0; m < 4; ++m) { const int row = row0 + ai * 128 + m * 16; xv[m] = *(const u32x4*)(X + (size_t)row * DM + col0 + bj * 128); st[m] = stat[row]; }
;                 __builtin_amdgcn_sched_barrier(0);
; #pragma unroll
;                 for (int m = 0; m < 4; ++m) {
;                     const f32x4 x0 = {hlo(xv[m].x), hhi(xv[m].x), hlo(xv[m].y), hhi(xv[m].y)}, x1 = {hlo(xv[m].z), hhi(xv[m].z), hlo(xv[m].w), hhi(xv[m].w)};
;                     const f32x4 y0 = (x0 - st[m].x) * st[m].y * gq[0] + bq[0] + gs[0] * acc[ai][bj][m][0];
;                     const f32x4 y1 = (x1 - st[m].x) * st[m].y * gq[1] + bq[1] + gs[1] * acc[ai][bj][m][1];
;                     u32x4 w; w.x = pkh2(y0.x, y0.y); w.y = pkh2(y0.z, y0.w); w.z = pkh2(y1.x, y1.y); w.w = pkh2(y1.z, y1.w);
;                     *(u32x4*)(X + (size_t)(row0 + ai * 128 + m * 16) * DM + col0 + bj * 128) = w;
;                 }
	v_sub_f32_e32 v56, v56, v126
	v_sub_f32_e32 v57, v57, v126
	v_sub_f32_e32 v58, v58, v126
	v_sub_f32_e32 v59, v59, v126
	v_pk_mul_f32 v[58:59], v[126:127], v[58:59] op_sel:[1,0]
	v_pk_mul_f32 v[56:57], v[126:127], v[56:57] op_sel:[1,0]
	v_pk_fma_f32 v[58:59], v[70:71], v[58:59], v[92:93]
	v_pk_fma_f32 v[56:57], v[74:75], v[56:57], v[94:95]
	v_pk_fma_f32 v[54:55], v[54:55], v[66:67], v[58:59]
	v_pk_fma_f32 v[52:53], v[52:53], v[68:69], v[56:57]
	v_sub_f32_e32 v56, v61, v126
	v_sub_f32_e32 v57, v60, v126
	v_sub_f32_e32 v58, v63, v126
	v_sub_f32_e32 v59, v62, v126
	v_pk_mul_f32 v[58:59], v[126:127], v[58:59] op_sel:[1,0]
	v_pk_mul_f32 v[56:57], v[126:127], v[56:57] op_sel:[1,0]
	v_pk_fma_f32 v[58:59], v[82:83], v[58:59], v[86:87]
	v_pk_fma_f32 v[56:57], v[84:85], v[56:57], v[90:91]
	v_pk_fma_f32 v[58:59], v[50:51], v[76:77], v[58:59]
	v_pk_fma_f32 v[50:51], v[48:49], v[78:79], v[56:57]
	v_cvt_pkrtz_f16_f32 v48, v52, v53
	v_cvt_pkrtz_f16_f32 v49, v54, v55
	v_cvt_pkrtz_f16_f32 v50, v50, v51
	v_cvt_pkrtz_f16_f32 v51, v58, v59
	global_store_dwordx4 v[112:113], v[48:51], off offset:256
	s_waitcnt vmcnt(5)
	v_cvt_f32_f16_sdwa v52, v124 dst_sel:DWORD dst_unused:UNUSED_PAD src0_sel:WORD_1
	v_cvt_f32_f16_e32 v53, v124
	v_cvt_f32_f16_sdwa v49, v122 dst_sel:DWORD dst_unused:UNUSED_PAD src0_sel:WORD_1
	v_cvt_f32_f16_e32 v48, v122
	v_cvt_f32_f16_sdwa v51, v123 dst_sel:DWORD dst_unused:UNUSED_PAD src0_sel:WORD_1
	v_cvt_f32_f16_e32 v50, v123
	v_cvt_f32_f16_sdwa v54, v125 dst_sel:DWORD dst_unused:UNUSED_PAD src0_sel:WORD_1
	v_cvt_f32_f16_e32 v55, v125
	s_waitcnt vmcnt(4)
	v_sub_f32_e32 v48, v48, v142
	v_sub_f32_e32 v49, v49, v142
	v_sub_f32_e32 v50, v50, v142
	v_sub_f32_e32 v51, v51, v142
	v_pk_mul_f32 v[50:51], v[142:143], v[50:51] op_sel:[1,0]
	v_pk_mul_f32 v[48:49], v[142:143], v[48:49] op_sel:[1,0]
	v_pk_fma_f32 v[50:51], v[70:71], v[50:51], v[92:93]
	v_pk_fma_f32 v[48:49], v[74:75], v[48:49], v[94:95]
	v_pk_fma_f32 v[46:47], v[46:47], v[66:67], v[50:51]
	v_pk_fma_f32 v[44:45], v[44:45], v[68:69], v[48:49]
	v_sub_f32_e32 v48, v53, v142
	v_sub_f32_e32 v49, v52, v142
	v_sub_f32_e32 v50, v55, v142
	v_sub_f32_e32 v51, v54, v142
	v_pk_mul_f32 v[50:51], v[142:143], v[50:51] op_sel:[1,0]
	v_pk_mul_f32 v[48:49], v[142:143], v[48:49] op_sel:[1,0]
	v_pk_fma_f32 v[50:51], v[82:83], v[50:51], v[86:87]
	v_pk_fma_f32 v[48:49], v[84:85], v[48:49], v[90:91]
	v_pk_fma_f32 v[50:51], v[42:43], v[76:77], v[50:51]
	v_pk_fma_f32 v[42:43], v[40:41], v[78:79], v[48:49]
	v_cvt_pkrtz_f16_f32 v40, v44, v45
	v_cvt_pkrtz_f16_f32 v41, v46, v47
	v_cvt_pkrtz_f16_f32 v42, v42, v43
	v_cvt_pkrtz_f16_f32 v43, v50, v51
	global_store_dwordx4 v[104:105], v[40:43], off offset:256
	s_waitcnt vmcnt(4)
	v_cvt_f32_f16_sdwa v44, v156 dst_sel:DWORD dst_unused:UNUSED_PAD src0_sel:WORD_1
	v_cvt_f32_f16_e32 v45, v156
	v_cvt_f32_f16_sdwa v41, v154 dst_sel:DWORD dst_unused:UNUSED_PAD src0_sel:WORD_1
	v_cvt_f32_f16_e32 v40, v154
	v_cvt_f32_f16_sdwa v43, v155 dst_sel:DWORD dst_unused:UNUSED_PAD src0_sel:WORD_1
	v_cvt_f32_f16_e32 v42, v155
	v_cvt_f32_f16_sdwa v46, v157 dst_sel:DWORD dst_unused:UNUSED_PAD src0_sel:WORD_1
	v_cvt_f32_f16_e32 v47, v157
	s_waitcnt vmcnt(3)
	v_sub_f32_e32 v40, v40, v150
	v_sub_f32_e32 v41, v41, v150
	v_sub_f32_e32 v42, v42, v150
	v_sub_f32_e32 v43, v43, v150
	v_pk_mul_f32 v[42:43], v[150:151], v[42:43] op_sel:[1,0]
	v_pk_mul_f32 v[40:41], v[150:151], v[40:41] op_sel:[1,0]
	v_pk_fma_f32 v[42:43], v[70:71], v[42:43], v[92:93]
	v_pk_fma_f32 v[40:41], v[74:75], v[40:41], v[94:95]
	v_pk_fma_f32 v[38:39], v[38:39], v[66:67], v[42:43]
	v_pk_fma_f32 v[36:37], v[36:37], v[68:69], v[40:41]
	v_sub_f32_e32 v40, v45, v150
	v_sub_f32_e32 v41, v44, v150
	v_sub_f32_e32 v42, v47, v150
	v_sub_f32_e32 v43, v46, v150
	v_pk_mul_f32 v[42:43], v[150:151], v[42:43] op_sel:[1,0]
	v_pk_mul_f32 v[40:41], v[150:151], v[40:41] op_sel:[1,0]
	v_pk_fma_f32 v[42:43], v[82:83], v[42:43], v[86:87]
	v_pk_fma_f32 v[40:41], v[84:85], v[40:41], v[90:91]
	v_pk_fma_f32 v[42:43], v[34:35], v[76:77], v[42:43]
	v_pk_fma_f32 v[34:35], v[32:33], v[78:79], v[40:41]
	v_cvt_pkrtz_f16_f32 v32, v36, v37
	v_cvt_pkrtz_f16_f32 v33, v38, v39
	v_cvt_pkrtz_f16_f32 v34, v34, v35
	v_cvt_pkrtz_f16_f32 v35, v42, v43
	global_store_dwordx4 v[96:97], v[32:35], off offset:256
	global_load_dwordx4 v[32:35], v[98:99], off offset:256
	s_nop 0
	global_load_dwordx4 v[36:39], v[100:101], off offset:256
	global_load_dwordx4 v[40:43], v[102:103], off offset:256
	global_load_dwordx4 v[44:47], v[106:107], off offset:256
	global_load_dwordx2 v[48:49], v[138:139], off offset:1024
	global_load_dwordx2 v[50:51], v[138:139], off offset:1152
	global_load_dwordx2 v[52:53], v[138:139], off offset:1280
	global_load_dwordx2 v[54:55], v[138:139], off offset:1408
	s_waitcnt vmcnt(7)
	v_cvt_f32_f16_sdwa v56, v32 dst_sel:DWORD dst_unused:UNUSED_PAD src0_sel:WORD_1
	v_cvt_f32_f16_e32 v32, v32
	v_cvt_f32_f16_sdwa v57, v33 dst_sel:DWORD dst_unused:UNUSED_PAD src0_sel:WORD_1
	v_cvt_f32_f16_e32 v58, v33
	v_cvt_f32_f16_sdwa v59, v34 dst_sel:DWORD dst_unused:UNUSED_PAD src0_sel:WORD_1
	v_cvt_f32_f16_e32 v60, v34
	v_cvt_f32_f16_sdwa v61, v35 dst_sel:DWORD dst_unused:UNUSED_PAD src0_sel:WORD_1
	v_cvt_f32_f16_e32 v62, v35
	s_waitcnt vmcnt(3)
; #define PG8_BAR __builtin_amdgcn_s_barrier()
; DI unsigned pkh2(float lo, float hi) { return __builtin_bit_cast(unsigned, __builtin_amdgcn_cvt_pkrtz(lo, hi)); }
; DI float hlo(unsigned u) { return (float)__builtin_bit_cast(f16x2_t, u).x; }
; DI float hhi(unsigned u) { return (float)__builtin_bit_cast(f16x2_t, u).y; }
; template <class Epi, class Sched, bool ALIGN_EPI = false, bool SP2 = false>
; __device__ __forceinline__ void gemm_phase(PG8_LAS unsigned char* lds, const Gemm g, const Sched& S, const Epi& E, const int tid) {
;     ...
;         if constexpr (ALIGN_EPI) { if (wr == 0) PG8_BAR; }
;         if constexpr (!Epi::AFTER_DRAIN) { E(acc, cur, wr, wc, fr, fq); S.done(cur); }
;         if (!has_next) break;
; #pragma unroll
;         for (int a = 0; a < 2; ++a)
; #pragma unroll
;             for (int b = 0; b < 2; ++b)
; #pragma unroll
;                 for (int m = 0; m < 4; ++m)
; #pragma unroll
;                     for (int n = 0; n < 2; ++n) acc[a][b][m][n] = (f32x4){0.f, 0.f, 0.f, 0.f};
;         cur = nxt; cA = nA; cB = nB; ++ui;
;         if constexpr (ALIGN_EPI) { if (wr == 1) PG8_BAR; }
;     }
;     DI void operator()(const pg8::f32x4 (&acc)[2][2][4][2], const pg8::Unit& u, int wr, int wc, int fr, int fq) const {
;     ...
;                 for (int m = 0; m < 4; ++m) { const int row = row0 + ai * 128 + m * 16; xv[m] = *(const u32x4*)(X + (size_t)row * DM + col0 + bj * 128); st[m] = stat[row]; }
;                 __builtin_amdgcn_sched_barrier(0);
; #pragma unroll
;                 for (int m = 0; m < 4; ++m) {
;                     const f32x4 x0 = {hlo(xv[m].x), hhi(xv[m].x), hlo(xv[m].y), hhi(xv[m].y)}, x1 = {hlo(xv[m].z), hhi(xv[m].z), hlo(xv[m].w), hhi(xv[m].w)};
;                     const f32x4 y0 = (x0 - st[m].x) * st[m].y * gq[0] + bq[0] + gs[0] * acc[ai][bj][m][0];
;                     const f32x4 y1 = (x1 - st[m].x) * st[m].y * gq[1] + bq[1] + gs[1] * acc[ai][bj][m][1];
;                     u32x4 w; w.x = pkh2(y0.x, y0.y); w.y = pkh2(y0.z, y0.w); w.z = pkh2(y1.x, y1.y); w.w = pkh2(y1.z, y1.w);
;                     *(u32x4*)(X + (size_t)(row0 + ai * 128 + m * 16) * DM + col0 + bj * 128) = w;
;                 }
;                 __builtin_amdgcn_sched_barrier(0);
;             }
;         }
	v_sub_f32_e32 v32, v32, v48
	v_sub_f32_e32 v33, v56, v48
	v_sub_f32_e32 v34, v58, v48
	v_sub_f32_e32 v35, v57, v48
	v_pk_mul_f32 v[34:35], v[48:49], v[34:35] op_sel:[1,0]
	v_pk_mul_f32 v[32:33], v[48:49], v[32:33] op_sel:[1,0]
	v_pk_fma_f32 v[34:35], v[70:71], v[34:35], v[92:93]
	v_pk_fma_f32 v[32:33], v[74:75], v[32:33], v[94:95]
	v_pk_fma_f32 v[30:31], v[30:31], v[66:67], v[34:35]
	v_pk_fma_f32 v[28:29], v[28:29], v[68:69], v[32:33]
	v_sub_f32_e32 v32, v60, v48
	v_sub_f32_e32 v33, v59, v48
	v_sub_f32_e32 v34, v62, v48
	v_sub_f32_e32 v35, v61, v48
	v_pk_mul_f32 v[34:35], v[48:49], v[34:35] op_sel:[1,0]
	v_pk_mul_f32 v[32:33], v[48:49], v[32:33] op_sel:[1,0]
	v_pk_fma_f32 v[34:35], v[82:83], v[34:35], v[86:87]
	v_pk_fma_f32 v[32:33], v[84:85], v[32:33], v[90:91]
	v_pk_fma_f32 v[34:35], v[26:27], v[76:77], v[34:35]
	v_pk_fma_f32 v[26:27], v[24:25], v[78:79], v[32:33]
	v_cvt_pkrtz_f16_f32 v24, v28, v29
	v_cvt_pkrtz_f16_f32 v25, v30, v31
	v_cvt_pkrtz_f16_f32 v26, v26, v27
	v_cvt_pkrtz_f16_f32 v27, v34, v35
	global_store_dwordx4 v[88:89], v[24:27], off offset:256
	v_cvt_f32_f16_sdwa v28, v38 dst_sel:DWORD dst_unused:UNUSED_PAD src0_sel:WORD_1
	v_cvt_f32_f16_e32 v29, v38
	v_cvt_f32_f16_sdwa v25, v36 dst_sel:DWORD dst_unused:UNUSED_PAD src0_sel:WORD_1
	v_cvt_f32_f16_e32 v24, v36
	v_cvt_f32_f16_sdwa v27, v37 dst_sel:DWORD dst_unused:UNUSED_PAD src0_sel:WORD_1
	v_cvt_f32_f16_e32 v26, v37
	v_cvt_f32_f16_sdwa v30, v39 dst_sel:DWORD dst_unused:UNUSED_PAD src0_sel:WORD_1
	v_cvt_f32_f16_e32 v31, v39
	s_waitcnt vmcnt(3)
	v_sub_f32_e32 v24, v24, v50
	v_sub_f32_e32 v25, v25, v50
	v_sub_f32_e32 v26, v26, v50
	v_sub_f32_e32 v27, v27, v50
	v_pk_mul_f32 v[26:27], v[50:51], v[26:27] op_sel:[1,0]
	v_pk_mul_f32 v[24:25], v[50:51], v[24:25] op_sel:[1,0]
	v_pk_fma_f32 v[26:27], v[70:71], v[26:27], v[92:93]
	v_pk_fma_f32 v[24:25], v[74:75], v[24:25], v[94:95]
	v_pk_fma_f32 v[22:23], v[22:23], v[66:67], v[26:27]
	v_pk_fma_f32 v[20:21], v[20:21], v[68:69], v[24:25]
	v_sub_f32_e32 v24, v29, v50
	v_sub_f32_e32 v25, v28, v50
	v_sub_f32_e32 v26, v31, v50
	v_sub_f32_e32 v27, v30, v50
	v_pk_mul_f32 v[26:27], v[50:51], v[26:27] op_sel:[1,0]
	v_pk_mul_f32 v[24:25], v[50:51], v[24:25] op_sel:[1,0]
	v_pk_fma_f32 v[26:27], v[82:83], v[26:27], v[86:87]
	v_pk_fma_f32 v[24:25], v[84:85], v[24:25], v[90:91]
	v_pk_fma_f32 v[26:27], v[18:19], v[76:77], v[26:27]
	v_pk_fma_f32 v[18:19], v[16:17], v[78:79], v[24:25]
	v_cvt_pkrtz_f16_f32 v16, v20, v21
	v_cvt_pkrtz_f16_f32 v17, v22, v23
	v_cvt_pkrtz_f16_f32 v18, v18, v19
	v_cvt_pkrtz_f16_f32 v19, v26, v27
	global_store_dwordx4 v[80:81], v[16:19], off offset:256
	v_cvt_f32_f16_sdwa v20, v42 dst_sel:DWORD dst_unused:UNUSED_PAD src0_sel:WORD_1
	v_cvt_f32_f16_e32 v21, v42
	v_cvt_f32_f16_sdwa v17, v40 dst_sel:DWORD dst_unused:UNUSED_PAD src0_sel:WORD_1
	v_cvt_f32_f16_e32 v16, v40
	v_cvt_f32_f16_sdwa v19, v41 dst_sel:DWORD dst_unused:UNUSED_PAD src0_sel:WORD_1
	v_cvt_f32_f16_e32 v18, v41
	v_cvt_f32_f16_sdwa v22, v43 dst_sel:DWORD dst_unused:UNUSED_PAD src0_sel:WORD_1
	v_cvt_f32_f16_e32 v23, v43
	s_waitcnt vmcnt(3)
	v_sub_f32_e32 v16, v16, v52
	v_sub_f32_e32 v17, v17, v52
	v_sub_f32_e32 v18, v18, v52
	v_sub_f32_e32 v19, v19, v52
	v_pk_mul_f32 v[18:19], v[52:53], v[18:19] op_sel:[1,0]
	v_pk_mul_f32 v[16:17], v[52:53], v[16:17] op_sel:[1,0]
	v_pk_fma_f32 v[18:19], v[70:71], v[18:19], v[92:93]
	v_pk_fma_f32 v[16:17], v[74:75], v[16:17], v[94:95]
	v_pk_fma_f32 v[14:15], v[14:15], v[66:67], v[18:19]
	v_pk_fma_f32 v[12:13], v[12:13], v[68:69], v[16:17]
	v_sub_f32_e32 v16, v21, v52
	v_sub_f32_e32 v17, v20, v52
	v_sub_f32_e32 v18, v23, v52
	v_sub_f32_e32 v19, v22, v52
	v_pk_mul_f32 v[18:19], v[52:53], v[18:19] op_sel:[1,0]
	v_pk_mul_f32 v[16:17], v[52:53], v[16:17] op_sel:[1,0]
	v_pk_fma_f32 v[18:19], v[82:83], v[18:19], v[86:87]
	v_pk_fma_f32 v[16:17], v[84:85], v[16:17], v[90:91]
	v_pk_fma_f32 v[18:19], v[10:11], v[76:77], v[18:19]
	v_pk_fma_f32 v[10:11], v[8:9], v[78:79], v[16:17]
	v_cvt_pkrtz_f16_f32 v8, v12, v13
	v_cvt_pkrtz_f16_f32 v9, v14, v15
	v_cvt_pkrtz_f16_f32 v10, v10, v11
	v_cvt_pkrtz_f16_f32 v11, v18, v19
	global_store_dwordx4 v[72:73], v[8:11], off offset:256
	v_cvt_f32_f16_sdwa v12, v46 dst_sel:DWORD dst_unused:UNUSED_PAD src0_sel:WORD_1
	v_cvt_f32_f16_e32 v13, v46
	v_cvt_f32_f16_sdwa v9, v44 dst_sel:DWORD dst_unused:UNUSED_PAD src0_sel:WORD_1
	v_cvt_f32_f16_e32 v8, v44
	v_cvt_f32_f16_sdwa v11, v45 dst_sel:DWORD dst_unused:UNUSED_PAD src0_sel:WORD_1
	v_cvt_f32_f16_e32 v10, v45
	v_cvt_f32_f16_sdwa v14, v47 dst_sel:DWORD dst_unused:UNUSED_PAD src0_sel:WORD_1
	v_cvt_f32_f16_e32 v15, v47
	s_waitcnt vmcnt(3)
	v_sub_f32_e32 v8, v8, v54
	v_sub_f32_e32 v9, v9, v54
	v_sub_f32_e32 v10, v10, v54
	v_sub_f32_e32 v11, v11, v54
	v_pk_mul_f32 v[10:11], v[54:55], v[10:11] op_sel:[1,0]
	v_pk_mul_f32 v[8:9], v[54:55], v[8:9] op_sel:[1,0]
	v_pk_fma_f32 v[10:11], v[70:71], v[10:11], v[92:93]
	v_pk_fma_f32 v[8:9], v[74:75], v[8:9], v[94:95]
	v_pk_fma_f32 v[6:7], v[6:7], v[66:67], v[10:11]
	v_pk_fma_f32 v[4:5], v[4:5], v[68:69], v[8:9]
	v_sub_f32_e32 v8, v13, v54
	v_sub_f32_e32 v9, v12, v54
	v_sub_f32_e32 v10, v15, v54
	v_sub_f32_e32 v11, v14, v54
	v_pk_mul_f32 v[10:11], v[54:55], v[10:11] op_sel:[1,0]
	v_pk_mul_f32 v[8:9], v[54:55], v[8:9] op_sel:[1,0]
	v_pk_fma_f32 v[10:11], v[82:83], v[10:11], v[86:87]
	v_pk_fma_f32 v[8:9], v[84:85], v[8:9], v[90:91]
	v_pk_fma_f32 v[10:11], v[2:3], v[76:77], v[10:11]
	v_pk_fma_f32 v[2:3], v[0:1], v[78:79], v[8:9]
	v_cvt_pkrtz_f16_f32 v0, v4, v5
	v_cvt_pkrtz_f16_f32 v1, v6, v7
	v_cvt_pkrtz_f16_f32 v2, v2, v3
	v_cvt_pkrtz_f16_f32 v3, v10, v11
	global_store_dwordx4 v[64:65], v[0:3], off offset:256
	s_and_b64 vcc, exec, s[0:1]
	s_mov_b64 s[0:1], -1
	s_cbranch_vccnz .LBB0_869
	s_andn2_b64 vcc, exec, s[18:19]
	s_cbranch_vccnz .LBB0_868
	s_barrier
	s_branch .LBB0_868
